# deferred epilogue atomics only (out-proj epilogue x loads left as compiled)
# speedup vs baseline: 1.0007x; 1.0007x over previous
; __device__ __forceinline__ unsigned cvt_pk_bf16(float lo, float hi) { unsigned r; asm volatile("v_cvt_pk_bf16_f32 %0, %1, %2" : "=v"(r) : "v"(lo), "v"(hi)); return r; }
;     __device__ __forceinline__ void final(const f32x4 (&acc)[2][2][4][2], const Unit& u, int ui, int wr, int wc, int fr, int fq) const {
;     ...
;             for (int m = 0; m < 4; ++m) { const int row = row0 + ai * HALF + m * 16; const float f = tab[(ui * 256 + ai * HALF + wr * 64 + m * 16 + fr) * 4 + 2];
;                 const float* src = (row < 16384 ? srcA + (size_t)row * 2048 : srcB + (size_t)(row - 16384) * 2048) + col0; float s = 0.f;
; #pragma unroll
;                 for (int bj = 0; bj < 2; ++bj) { const f32x4 v0 = acc[ai][bj][m][0] * f + __builtin_nontemporal_load((const f32x4*)(src + bj * HALF)), v1 = acc[ai][bj][m][1] * f + __builtin_nontemporal_load((const f32x4*)(src + bj * HALF + 4));
;                     s += (v0[0] * v0[0] + v0[1] * v0[1]) + (v0[2] * v0[2] + v0[3] * v0[3]) + (v1[0] * v1[0] + v1[1] * v1[1]) + (v1[2] * v1[2] + v1[3] * v1[3]);
;                     u32x4 w; w.x = cvt_pk_bf16(v0[0], v0[1]); w.y = cvt_pk_bf16(v0[2], v0[3]); w.z = cvt_pk_bf16(v1[0], v1[1]); w.w = cvt_pk_bf16(v1[2], v1[3]);
;                     *(u32x4*)(xb + (size_t)row * 2048 + col0 + bj * HALF) = w; }
;                 s = sum_x32(sum_x16(s)); asm volatile("" : "+v"(s));
;                 if (fq == 0) atomicAdd(ss + row, s); }
.LBB0_423:
	ds_read_b32 v152, v163 offset:8
	v_lshl_add_u32 v150, s30, 8, v1
	v_cmp_lt_i32_e32 vcc, s67, v150
	s_and_saveexec_b64 s[30:31], vcc
	s_xor_b64 s[30:31], exec, s[30:31]
	v_add_u32_e32 v4, 0xffffc000, v150
	v_mov_b32_e32 v5, v2
	v_lshlrev_b64 v[4:5], 13, v[4:5]
	v_lshl_add_u64 v[154:155], s[38:39], 0, v[4:5]
	v_mov_b32_e32 v151, v2
	s_andn2_saveexec_b64 s[30:31], s[30:31]
	v_ashrrev_i32_e32 v151, 31, v150
	v_lshlrev_b64 v[4:5], 13, v[150:151]
	v_lshl_add_u64 v[154:155], s[36:37], 0, v[4:5]
	s_or_b64 exec, exec, s[30:31]
	v_lshl_or_b32 v4, s28, 8, v159
	v_ashrrev_i32_e32 v5, 31, v4
	v_lshl_add_u64 v[154:155], v[4:5], 2, v[154:155]
	global_load_dwordx4 v[164:167], v[154:155], off nt
	global_load_dwordx4 v[168:171], v[154:155], off offset:16 nt
	v_lshlrev_b64 v[172:173], 12, v[150:151]
	v_lshl_add_u64 v[172:173], s[16:17], 0, v[172:173]
	v_lshl_add_u64 v[172:173], v[4:5], 1, v[172:173]
	s_waitcnt vmcnt(0) lgkmcnt(0)
	v_pk_fma_f32 v[166:167], v[132:133], v[152:153], v[166:167] op_sel_hi:[1,0,1]
	v_pk_fma_f32 v[164:165], v[130:131], v[152:153], v[164:165] op_sel_hi:[1,0,1]
	v_pk_fma_f32 v[170:171], v[128:129], v[152:153], v[170:171] op_sel_hi:[1,0,1]
	v_pk_fma_f32 v[168:169], v[126:127], v[152:153], v[168:169] op_sel_hi:[1,0,1]
	v_cvt_pk_bf16_f32 v126, v164, v165
	v_cvt_pk_bf16_f32 v127, v166, v167
	v_mul_f32_e32 v153, v167, v167
	v_cvt_pk_bf16_f32 v128, v168, v169
	v_cvt_pk_bf16_f32 v129, v170, v171
	global_store_dwordx4 v[172:173], v[126:129], off
	global_load_dwordx4 v[126:129], v[154:155], off offset:512 nt
	s_nop 0
	global_load_dwordx4 v[130:133], v[154:155], off offset:528 nt
	v_fmac_f32_e32 v153, v166, v166
	v_mul_f32_e32 v3, v165, v165
	v_mul_f32_e32 v154, v169, v169
	v_fmac_f32_e32 v3, v164, v164
	v_mul_f32_e32 v155, v171, v171
	v_fmac_f32_e32 v154, v168, v168
	v_add_f32_e32 v3, v3, v153
	v_fmac_f32_e32 v155, v170, v170
	v_add_f32_e32 v3, v3, v154
	v_add_f32_e32 v3, v155, v3
	s_waitcnt vmcnt(1)
	v_pk_fma_f32 v[124:125], v[124:125], v[152:153], v[128:129] op_sel_hi:[1,0,1]
	v_pk_fma_f32 v[122:123], v[122:123], v[152:153], v[126:127] op_sel_hi:[1,0,1]
	s_waitcnt vmcnt(0)
	v_pk_fma_f32 v[128:129], v[118:119], v[152:153], v[130:131] op_sel_hi:[1,0,1]
	v_mul_f32_e32 v130, v123, v123
	v_mul_f32_e32 v131, v125, v125
	v_pk_fma_f32 v[126:127], v[120:121], v[152:153], v[132:133] op_sel_hi:[1,0,1]
	v_mul_f32_e32 v132, v129, v129
	v_cvt_pk_bf16_f32 v118, v122, v123
	v_fmac_f32_e32 v130, v122, v122
	v_fmac_f32_e32 v131, v124, v124
	v_mul_f32_e32 v133, v127, v127
	v_cvt_pk_bf16_f32 v119, v124, v125
	v_cvt_pk_bf16_f32 v120, v128, v129
	v_cvt_pk_bf16_f32 v121, v126, v127
	v_fmac_f32_e32 v132, v128, v128
	global_store_dwordx4 v[172:173], v[118:121], off offset:256
	v_fmac_f32_e32 v133, v126, v126
	s_nop 0
	v_add_f32_e32 v118, v130, v131
	v_add_f32_e32 v118, v118, v132
	v_add_f32_e32 v118, v133, v118
	v_add_f32_e32 v3, v3, v118
	v_mov_b32_e32 v118, v3
	s_nop 1
	v_permlane16_swap_b32_e32 v3, v118
	v_add_f32_e32 v3, v3, v118
	v_mov_b32_e32 v118, v3
	s_nop 1
	v_permlane32_swap_b32_e32 v3, v118
	v_add_f32_e32 v3, v3, v118
	v_mov_b32_e32 v226, v3
	v_lshl_add_u64 v[250:251], v[150:151], 2, s[18:19]
	ds_read_b32 v120, v163 offset:264
	v_or_b32_e32 v118, 16, v150
	v_cmp_lt_i32_e32 vcc, s67, v118
	s_and_saveexec_b64 s[28:29], vcc
	s_xor_b64 s[28:29], exec, s[28:29]
	v_add_u32_e32 v122, 0xffffc010, v150
	v_mov_b32_e32 v123, v2
	v_lshlrev_b64 v[122:123], 13, v[122:123]
	v_lshl_add_u64 v[122:123], s[38:39], 0, v[122:123]
	v_mov_b32_e32 v119, v2
	s_andn2_saveexec_b64 s[28:29], s[28:29]
	v_ashrrev_i32_e32 v119, 31, v118
	v_lshlrev_b64 v[122:123], 13, v[118:119]
	v_lshl_add_u64 v[122:123], s[36:37], 0, v[122:123]
	s_or_b64 exec, exec, s[28:29]
	v_lshl_add_u64 v[130:131], v[4:5], 2, v[122:123]
	global_load_dwordx4 v[122:125], v[130:131], off nt
	global_load_dwordx4 v[126:129], v[130:131], off offset:16 nt
	v_lshlrev_b64 v[132:133], 12, v[118:119]
	v_lshl_add_u64 v[132:133], s[16:17], 0, v[132:133]
	v_lshl_add_u64 v[132:133], v[4:5], 1, v[132:133]
	s_waitcnt vmcnt(1) lgkmcnt(0)
	v_pk_fma_f32 v[124:125], v[116:117], v[120:121], v[124:125] op_sel_hi:[1,0,1]
	v_pk_fma_f32 v[122:123], v[114:115], v[120:121], v[122:123] op_sel_hi:[1,0,1]
	s_waitcnt vmcnt(0)
	v_pk_fma_f32 v[128:129], v[112:113], v[120:121], v[128:129] op_sel_hi:[1,0,1]
	v_pk_fma_f32 v[126:127], v[110:111], v[120:121], v[126:127] op_sel_hi:[1,0,1]
	v_cvt_pk_bf16_f32 v110, v122, v123
	v_cvt_pk_bf16_f32 v111, v124, v125
	v_mul_f32_e32 v121, v125, v125
	v_cvt_pk_bf16_f32 v112, v126, v127
	v_cvt_pk_bf16_f32 v113, v128, v129
	global_store_dwordx4 v[132:133], v[110:113], off
	global_load_dwordx4 v[110:113], v[130:131], off offset:512 nt
	s_nop 0
	global_load_dwordx4 v[114:117], v[130:131], off offset:528 nt
	v_fmac_f32_e32 v121, v124, v124
	v_mul_f32_e32 v3, v123, v123
	v_mul_f32_e32 v123, v127, v127
	v_fmac_f32_e32 v3, v122, v122
	v_mul_f32_e32 v125, v129, v129
	v_fmac_f32_e32 v123, v126, v126
	v_add_f32_e32 v3, v3, v121
	v_fmac_f32_e32 v125, v128, v128
	v_add_f32_e32 v3, v3, v123
	v_add_f32_e32 v3, v125, v3
	s_waitcnt vmcnt(1)
	v_pk_fma_f32 v[108:109], v[108:109], v[120:121], v[112:113] op_sel_hi:[1,0,1]
	v_pk_fma_f32 v[106:107], v[106:107], v[120:121], v[110:111] op_sel_hi:[1,0,1]
	s_waitcnt vmcnt(0)
; __device__ __forceinline__ unsigned cvt_pk_bf16(float lo, float hi) { unsigned r; asm volatile("v_cvt_pk_bf16_f32 %0, %1, %2" : "=v"(r) : "v"(lo), "v"(hi)); return r; }
;     __device__ __forceinline__ void final(const f32x4 (&acc)[2][2][4][2], const Unit& u, int ui, int wr, int wc, int fr, int fq) const {
;     ...
;             for (int m = 0; m < 4; ++m) { const int row = row0 + ai * HALF + m * 16; const float f = tab[(ui * 256 + ai * HALF + wr * 64 + m * 16 + fr) * 4 + 2];
;                 const float* src = (row < 16384 ? srcA + (size_t)row * 2048 : srcB + (size_t)(row - 16384) * 2048) + col0; float s = 0.f;
; #pragma unroll
;                 for (int bj = 0; bj < 2; ++bj) { const f32x4 v0 = acc[ai][bj][m][0] * f + __builtin_nontemporal_load((const f32x4*)(src + bj * HALF)), v1 = acc[ai][bj][m][1] * f + __builtin_nontemporal_load((const f32x4*)(src + bj * HALF + 4));
;                     s += (v0[0] * v0[0] + v0[1] * v0[1]) + (v0[2] * v0[2] + v0[3] * v0[3]) + (v1[0] * v1[0] + v1[1] * v1[1]) + (v1[2] * v1[2] + v1[3] * v1[3]);
;                     u32x4 w; w.x = cvt_pk_bf16(v0[0], v0[1]); w.y = cvt_pk_bf16(v0[2], v0[3]); w.z = cvt_pk_bf16(v1[0], v1[1]); w.w = cvt_pk_bf16(v1[2], v1[3]);
;                     *(u32x4*)(xb + (size_t)row * 2048 + col0 + bj * HALF) = w; }
;                 s = sum_x32(sum_x16(s)); asm volatile("" : "+v"(s));
;                 if (fq == 0) atomicAdd(ss + row, s); }
	v_pk_fma_f32 v[112:113], v[102:103], v[120:121], v[114:115] op_sel_hi:[1,0,1]
	v_mul_f32_e32 v114, v107, v107
	v_mul_f32_e32 v115, v109, v109
	v_pk_fma_f32 v[110:111], v[104:105], v[120:121], v[116:117] op_sel_hi:[1,0,1]
	v_mul_f32_e32 v116, v113, v113
	v_cvt_pk_bf16_f32 v102, v106, v107
	v_fmac_f32_e32 v114, v106, v106
	v_fmac_f32_e32 v115, v108, v108
	v_mul_f32_e32 v117, v111, v111
	v_cvt_pk_bf16_f32 v103, v108, v109
	v_cvt_pk_bf16_f32 v104, v112, v113
	v_cvt_pk_bf16_f32 v105, v110, v111
	v_fmac_f32_e32 v116, v112, v112
	global_store_dwordx4 v[132:133], v[102:105], off offset:256
	v_fmac_f32_e32 v117, v110, v110
	s_nop 0
	v_add_f32_e32 v102, v114, v115
	v_add_f32_e32 v102, v102, v116
	v_add_f32_e32 v102, v117, v102
	v_add_f32_e32 v3, v3, v102
	v_mov_b32_e32 v102, v3
	s_nop 1
	v_permlane16_swap_b32_e32 v3, v102
	v_add_f32_e32 v3, v3, v102
	v_mov_b32_e32 v102, v3
	s_nop 1
	v_permlane32_swap_b32_e32 v3, v102
	v_add_f32_e32 v3, v3, v102
	v_mov_b32_e32 v227, v3
	ds_read_b32 v104, v163 offset:520
	v_or_b32_e32 v102, 32, v150
	v_cmp_lt_i32_e32 vcc, s67, v102
	s_and_saveexec_b64 s[28:29], vcc
	s_xor_b64 s[28:29], exec, s[28:29]
	v_add_u32_e32 v106, 0xffffc020, v150
	v_mov_b32_e32 v107, v2
	v_lshlrev_b64 v[106:107], 13, v[106:107]
	v_lshl_add_u64 v[106:107], s[38:39], 0, v[106:107]
	v_mov_b32_e32 v103, v2
	s_andn2_saveexec_b64 s[28:29], s[28:29]
	v_ashrrev_i32_e32 v103, 31, v102
	v_lshlrev_b64 v[106:107], 13, v[102:103]
	v_lshl_add_u64 v[106:107], s[36:37], 0, v[106:107]
	s_or_b64 exec, exec, s[28:29]
	v_lshl_add_u64 v[114:115], v[4:5], 2, v[106:107]
	global_load_dwordx4 v[106:109], v[114:115], off nt
	global_load_dwordx4 v[110:113], v[114:115], off offset:16 nt
	v_lshlrev_b64 v[116:117], 12, v[102:103]
	v_lshl_add_u64 v[116:117], s[16:17], 0, v[116:117]
	v_lshl_add_u64 v[116:117], v[4:5], 1, v[116:117]
	s_waitcnt vmcnt(1) lgkmcnt(0)
	v_pk_fma_f32 v[108:109], v[100:101], v[104:105], v[108:109] op_sel_hi:[1,0,1]
	v_pk_fma_f32 v[106:107], v[98:99], v[104:105], v[106:107] op_sel_hi:[1,0,1]
	s_waitcnt vmcnt(0)
	v_pk_fma_f32 v[112:113], v[96:97], v[104:105], v[112:113] op_sel_hi:[1,0,1]
	v_pk_fma_f32 v[110:111], v[94:95], v[104:105], v[110:111] op_sel_hi:[1,0,1]
	v_cvt_pk_bf16_f32 v94, v106, v107
	v_cvt_pk_bf16_f32 v95, v108, v109
	v_mul_f32_e32 v105, v109, v109
	v_cvt_pk_bf16_f32 v96, v110, v111
	v_cvt_pk_bf16_f32 v97, v112, v113
	global_store_dwordx4 v[116:117], v[94:97], off
	global_load_dwordx4 v[94:97], v[114:115], off offset:512 nt
	s_nop 0
	global_load_dwordx4 v[98:101], v[114:115], off offset:528 nt
	v_fmac_f32_e32 v105, v108, v108
	v_mul_f32_e32 v3, v107, v107
	v_mul_f32_e32 v107, v111, v111
	v_fmac_f32_e32 v3, v106, v106
	v_mul_f32_e32 v109, v113, v113
	v_fmac_f32_e32 v107, v110, v110
	v_add_f32_e32 v3, v3, v105
	v_fmac_f32_e32 v109, v112, v112
	v_add_f32_e32 v3, v3, v107
	v_add_f32_e32 v3, v109, v3
	s_waitcnt vmcnt(1)
	v_pk_fma_f32 v[92:93], v[92:93], v[104:105], v[96:97] op_sel_hi:[1,0,1]
	v_pk_fma_f32 v[90:91], v[90:91], v[104:105], v[94:95] op_sel_hi:[1,0,1]
	s_waitcnt vmcnt(0)
	v_pk_fma_f32 v[96:97], v[86:87], v[104:105], v[98:99] op_sel_hi:[1,0,1]
	v_mul_f32_e32 v98, v91, v91
	v_mul_f32_e32 v99, v93, v93
	v_pk_fma_f32 v[94:95], v[88:89], v[104:105], v[100:101] op_sel_hi:[1,0,1]
	v_mul_f32_e32 v100, v97, v97
	v_cvt_pk_bf16_f32 v86, v90, v91
	v_fmac_f32_e32 v98, v90, v90
	v_fmac_f32_e32 v99, v92, v92
	v_mul_f32_e32 v101, v95, v95
	v_cvt_pk_bf16_f32 v87, v92, v93
	v_cvt_pk_bf16_f32 v88, v96, v97
	v_cvt_pk_bf16_f32 v89, v94, v95
	v_fmac_f32_e32 v100, v96, v96
	global_store_dwordx4 v[116:117], v[86:89], off offset:256
	v_fmac_f32_e32 v101, v94, v94
	s_nop 0
	v_add_f32_e32 v86, v98, v99
	v_add_f32_e32 v86, v86, v100
	v_add_f32_e32 v86, v101, v86
	v_add_f32_e32 v3, v3, v86
	v_mov_b32_e32 v86, v3
	s_nop 1
	v_permlane16_swap_b32_e32 v3, v86
	v_add_f32_e32 v3, v3, v86
	v_mov_b32_e32 v86, v3
	s_nop 1
	v_permlane32_swap_b32_e32 v3, v86
	v_add_f32_e32 v3, v3, v86
	v_mov_b32_e32 v228, v3
	ds_read_b32 v88, v163 offset:776
	v_or_b32_e32 v86, 48, v150
	v_cmp_lt_i32_e32 vcc, s67, v86
	s_and_saveexec_b64 s[28:29], vcc
	s_xor_b64 s[28:29], exec, s[28:29]
	v_add_u32_e32 v90, 0xffffc030, v150
	v_mov_b32_e32 v91, v2
	v_lshlrev_b64 v[90:91], 13, v[90:91]
	v_lshl_add_u64 v[90:91], s[38:39], 0, v[90:91]
	v_mov_b32_e32 v87, v2
	s_andn2_saveexec_b64 s[28:29], s[28:29]
	v_ashrrev_i32_e32 v87, 31, v86
	v_lshlrev_b64 v[90:91], 13, v[86:87]
	v_lshl_add_u64 v[90:91], s[36:37], 0, v[90:91]
	s_or_b64 exec, exec, s[28:29]
	v_lshl_add_u64 v[98:99], v[4:5], 2, v[90:91]
	global_load_dwordx4 v[90:93], v[98:99], off nt
	global_load_dwordx4 v[94:97], v[98:99], off offset:16 nt
	v_lshlrev_b64 v[100:101], 12, v[86:87]
	v_lshl_add_u64 v[100:101], s[16:17], 0, v[100:101]
	v_lshl_add_u64 v[100:101], v[4:5], 1, v[100:101]
	s_waitcnt vmcnt(1) lgkmcnt(0)
	v_pk_fma_f32 v[92:93], v[84:85], v[88:89], v[92:93] op_sel_hi:[1,0,1]
	v_pk_fma_f32 v[90:91], v[82:83], v[88:89], v[90:91] op_sel_hi:[1,0,1]
	s_waitcnt vmcnt(0)
	v_pk_fma_f32 v[96:97], v[80:81], v[88:89], v[96:97] op_sel_hi:[1,0,1]
	v_pk_fma_f32 v[94:95], v[78:79], v[88:89], v[94:95] op_sel_hi:[1,0,1]
	v_cvt_pk_bf16_f32 v78, v90, v91
	v_cvt_pk_bf16_f32 v79, v92, v93
	v_mul_f32_e32 v89, v93, v93
	v_cvt_pk_bf16_f32 v80, v94, v95
	v_cvt_pk_bf16_f32 v81, v96, v97
	global_store_dwordx4 v[100:101], v[78:81], off
	global_load_dwordx4 v[78:81], v[98:99], off offset:512 nt
	s_nop 0
	global_load_dwordx4 v[82:85], v[98:99], off offset:528 nt
	v_fmac_f32_e32 v89, v92, v92
	v_mul_f32_e32 v3, v91, v91
	v_mul_f32_e32 v91, v95, v95
	v_fmac_f32_e32 v3, v90, v90
	v_mul_f32_e32 v93, v97, v97
	v_fmac_f32_e32 v91, v94, v94
	v_add_f32_e32 v3, v3, v89
	v_fmac_f32_e32 v93, v96, v96
	v_add_f32_e32 v3, v3, v91
	v_add_f32_e32 v3, v93, v3
	s_waitcnt vmcnt(1)
; __device__ __forceinline__ unsigned cvt_pk_bf16(float lo, float hi) { unsigned r; asm volatile("v_cvt_pk_bf16_f32 %0, %1, %2" : "=v"(r) : "v"(lo), "v"(hi)); return r; }
;     __device__ __forceinline__ void final(const f32x4 (&acc)[2][2][4][2], const Unit& u, int ui, int wr, int wc, int fr, int fq) const {
;     ...
;             for (int m = 0; m < 4; ++m) { const int row = row0 + ai * HALF + m * 16; const float f = tab[(ui * 256 + ai * HALF + wr * 64 + m * 16 + fr) * 4 + 2];
;                 const float* src = (row < 16384 ? srcA + (size_t)row * 2048 : srcB + (size_t)(row - 16384) * 2048) + col0; float s = 0.f;
; #pragma unroll
;                 for (int bj = 0; bj < 2; ++bj) { const f32x4 v0 = acc[ai][bj][m][0] * f + __builtin_nontemporal_load((const f32x4*)(src + bj * HALF)), v1 = acc[ai][bj][m][1] * f + __builtin_nontemporal_load((const f32x4*)(src + bj * HALF + 4));
;                     s += (v0[0] * v0[0] + v0[1] * v0[1]) + (v0[2] * v0[2] + v0[3] * v0[3]) + (v1[0] * v1[0] + v1[1] * v1[1]) + (v1[2] * v1[2] + v1[3] * v1[3]);
;                     u32x4 w; w.x = cvt_pk_bf16(v0[0], v0[1]); w.y = cvt_pk_bf16(v0[2], v0[3]); w.z = cvt_pk_bf16(v1[0], v1[1]); w.w = cvt_pk_bf16(v1[2], v1[3]);
;                     *(u32x4*)(xb + (size_t)row * 2048 + col0 + bj * HALF) = w; }
;                 s = sum_x32(sum_x16(s)); asm volatile("" : "+v"(s));
;                 if (fq == 0) atomicAdd(ss + row, s); }
	v_pk_fma_f32 v[76:77], v[76:77], v[88:89], v[80:81] op_sel_hi:[1,0,1]
	v_pk_fma_f32 v[74:75], v[74:75], v[88:89], v[78:79] op_sel_hi:[1,0,1]
	s_waitcnt vmcnt(0)
	v_pk_fma_f32 v[80:81], v[70:71], v[88:89], v[82:83] op_sel_hi:[1,0,1]
	v_mul_f32_e32 v82, v75, v75
	v_mul_f32_e32 v83, v77, v77
	v_pk_fma_f32 v[78:79], v[72:73], v[88:89], v[84:85] op_sel_hi:[1,0,1]
	v_mul_f32_e32 v84, v81, v81
	v_cvt_pk_bf16_f32 v70, v74, v75
	v_fmac_f32_e32 v82, v74, v74
	v_fmac_f32_e32 v83, v76, v76
	v_mul_f32_e32 v85, v79, v79
	v_cvt_pk_bf16_f32 v71, v76, v77
	v_cvt_pk_bf16_f32 v72, v80, v81
	v_cvt_pk_bf16_f32 v73, v78, v79
	v_fmac_f32_e32 v84, v80, v80
	global_store_dwordx4 v[100:101], v[70:73], off offset:256
	v_fmac_f32_e32 v85, v78, v78
	s_nop 0
	v_add_f32_e32 v70, v82, v83
	v_add_f32_e32 v70, v70, v84
	v_add_f32_e32 v70, v85, v70
	v_add_f32_e32 v3, v3, v70
	v_mov_b32_e32 v70, v3
	s_nop 1
	v_permlane16_swap_b32_e32 v3, v70
	v_add_f32_e32 v3, v3, v70
	v_mov_b32_e32 v70, v3
	s_nop 1
	v_permlane32_swap_b32_e32 v3, v70
	v_add_f32_e32 v3, v3, v70
	v_mov_b32_e32 v229, v3
	ds_read_b32 v72, v163 offset:2056
	v_add_u32_e32 v70, 0x80, v150
	v_cmp_lt_i32_e32 vcc, s80, v150
	s_and_saveexec_b64 s[28:29], vcc
	s_xor_b64 s[28:29], exec, s[28:29]
	v_add_u32_e32 v74, 0xffffc080, v150
	v_mov_b32_e32 v75, v2
	v_lshlrev_b64 v[74:75], 13, v[74:75]
	v_lshl_add_u64 v[74:75], s[38:39], 0, v[74:75]
	v_mov_b32_e32 v71, v2
	s_andn2_saveexec_b64 s[28:29], s[28:29]
	v_ashrrev_i32_e32 v71, 31, v70
	v_lshlrev_b64 v[74:75], 13, v[70:71]
	v_lshl_add_u64 v[74:75], s[36:37], 0, v[74:75]
	s_or_b64 exec, exec, s[28:29]
	v_lshl_add_u64 v[82:83], v[4:5], 2, v[74:75]
	global_load_dwordx4 v[74:77], v[82:83], off nt
	global_load_dwordx4 v[78:81], v[82:83], off offset:16 nt
	v_lshlrev_b64 v[84:85], 12, v[70:71]
	v_lshl_add_u64 v[84:85], s[16:17], 0, v[84:85]
	v_lshl_add_u64 v[84:85], v[4:5], 1, v[84:85]
	s_waitcnt vmcnt(1) lgkmcnt(0)
	v_pk_fma_f32 v[76:77], v[68:69], v[72:73], v[76:77] op_sel_hi:[1,0,1]
	v_pk_fma_f32 v[74:75], v[66:67], v[72:73], v[74:75] op_sel_hi:[1,0,1]
	s_waitcnt vmcnt(0)
	v_pk_fma_f32 v[80:81], v[64:65], v[72:73], v[80:81] op_sel_hi:[1,0,1]
	v_pk_fma_f32 v[78:79], v[62:63], v[72:73], v[78:79] op_sel_hi:[1,0,1]
	v_cvt_pk_bf16_f32 v62, v74, v75
	v_cvt_pk_bf16_f32 v63, v76, v77
	v_mul_f32_e32 v73, v77, v77
	v_cvt_pk_bf16_f32 v64, v78, v79
	v_cvt_pk_bf16_f32 v65, v80, v81
	global_store_dwordx4 v[84:85], v[62:65], off
	global_load_dwordx4 v[62:65], v[82:83], off offset:512 nt
	s_nop 0
	global_load_dwordx4 v[66:69], v[82:83], off offset:528 nt
	v_fmac_f32_e32 v73, v76, v76
	v_mul_f32_e32 v3, v75, v75
	v_mul_f32_e32 v75, v79, v79
	v_fmac_f32_e32 v3, v74, v74
	v_mul_f32_e32 v77, v81, v81
	v_fmac_f32_e32 v75, v78, v78
	v_add_f32_e32 v3, v3, v73
	v_fmac_f32_e32 v77, v80, v80
	v_add_f32_e32 v3, v3, v75
	v_add_f32_e32 v3, v77, v3
	s_waitcnt vmcnt(1)
	v_pk_fma_f32 v[60:61], v[60:61], v[72:73], v[64:65] op_sel_hi:[1,0,1]
	v_pk_fma_f32 v[58:59], v[58:59], v[72:73], v[62:63] op_sel_hi:[1,0,1]
	s_waitcnt vmcnt(0)
	v_pk_fma_f32 v[64:65], v[54:55], v[72:73], v[66:67] op_sel_hi:[1,0,1]
	v_mul_f32_e32 v66, v59, v59
	v_mul_f32_e32 v67, v61, v61
	v_pk_fma_f32 v[62:63], v[56:57], v[72:73], v[68:69] op_sel_hi:[1,0,1]
	v_mul_f32_e32 v68, v65, v65
	v_cvt_pk_bf16_f32 v54, v58, v59
	v_fmac_f32_e32 v66, v58, v58
	v_fmac_f32_e32 v67, v60, v60
	v_mul_f32_e32 v69, v63, v63
	v_cvt_pk_bf16_f32 v55, v60, v61
	v_cvt_pk_bf16_f32 v56, v64, v65
	v_cvt_pk_bf16_f32 v57, v62, v63
	v_fmac_f32_e32 v68, v64, v64
	global_store_dwordx4 v[84:85], v[54:57], off offset:256
	v_fmac_f32_e32 v69, v62, v62
	s_nop 0
	v_add_f32_e32 v54, v66, v67
	v_add_f32_e32 v54, v54, v68
	v_add_f32_e32 v54, v69, v54
	v_add_f32_e32 v3, v3, v54
	v_mov_b32_e32 v54, v3
	s_nop 1
	v_permlane16_swap_b32_e32 v3, v54
	v_add_f32_e32 v3, v3, v54
	v_mov_b32_e32 v54, v3
	s_nop 1
	v_permlane32_swap_b32_e32 v3, v54
	v_add_f32_e32 v3, v3, v54
	v_mov_b32_e32 v230, v3
	ds_read_b32 v56, v163 offset:2312
	v_add_u32_e32 v54, 0x90, v150
	v_cmp_lt_i32_e32 vcc, s81, v150
	s_and_saveexec_b64 s[28:29], vcc
	s_xor_b64 s[28:29], exec, s[28:29]
	v_add_u32_e32 v58, 0xffffc090, v150
	v_mov_b32_e32 v59, v2
	v_lshlrev_b64 v[58:59], 13, v[58:59]
	v_lshl_add_u64 v[58:59], s[38:39], 0, v[58:59]
	v_mov_b32_e32 v55, v2
	s_andn2_saveexec_b64 s[28:29], s[28:29]
	v_ashrrev_i32_e32 v55, 31, v54
	v_lshlrev_b64 v[58:59], 13, v[54:55]
	v_lshl_add_u64 v[58:59], s[36:37], 0, v[58:59]
	s_or_b64 exec, exec, s[28:29]
	v_lshl_add_u64 v[66:67], v[4:5], 2, v[58:59]
	global_load_dwordx4 v[58:61], v[66:67], off nt
	global_load_dwordx4 v[62:65], v[66:67], off offset:16 nt
	v_lshlrev_b64 v[68:69], 12, v[54:55]
	v_lshl_add_u64 v[68:69], s[16:17], 0, v[68:69]
	v_lshl_add_u64 v[68:69], v[4:5], 1, v[68:69]
	s_waitcnt vmcnt(1) lgkmcnt(0)
	v_pk_fma_f32 v[60:61], v[52:53], v[56:57], v[60:61] op_sel_hi:[1,0,1]
	v_pk_fma_f32 v[58:59], v[50:51], v[56:57], v[58:59] op_sel_hi:[1,0,1]
	s_waitcnt vmcnt(0)
	v_pk_fma_f32 v[64:65], v[48:49], v[56:57], v[64:65] op_sel_hi:[1,0,1]
	v_pk_fma_f32 v[62:63], v[46:47], v[56:57], v[62:63] op_sel_hi:[1,0,1]
	v_cvt_pk_bf16_f32 v46, v58, v59
	v_cvt_pk_bf16_f32 v47, v60, v61
	v_mul_f32_e32 v57, v61, v61
	v_cvt_pk_bf16_f32 v48, v62, v63
	v_cvt_pk_bf16_f32 v49, v64, v65
	global_store_dwordx4 v[68:69], v[46:49], off
	global_load_dwordx4 v[46:49], v[66:67], off offset:512 nt
	s_nop 0
	global_load_dwordx4 v[50:53], v[66:67], off offset:528 nt
	v_fmac_f32_e32 v57, v60, v60
	v_mul_f32_e32 v3, v59, v59
	v_mul_f32_e32 v59, v63, v63
	v_fmac_f32_e32 v3, v58, v58
	v_mul_f32_e32 v61, v65, v65
	v_fmac_f32_e32 v59, v62, v62
	v_add_f32_e32 v3, v3, v57
	v_fmac_f32_e32 v61, v64, v64
	v_add_f32_e32 v3, v3, v59
	v_add_f32_e32 v3, v61, v3
	s_waitcnt vmcnt(1)
; __device__ __forceinline__ unsigned cvt_pk_bf16(float lo, float hi) { unsigned r; asm volatile("v_cvt_pk_bf16_f32 %0, %1, %2" : "=v"(r) : "v"(lo), "v"(hi)); return r; }
;     __device__ __forceinline__ void final(const f32x4 (&acc)[2][2][4][2], const Unit& u, int ui, int wr, int wc, int fr, int fq) const {
;     ...
;             for (int m = 0; m < 4; ++m) { const int row = row0 + ai * HALF + m * 16; const float f = tab[(ui * 256 + ai * HALF + wr * 64 + m * 16 + fr) * 4 + 2];
;                 const float* src = (row < 16384 ? srcA + (size_t)row * 2048 : srcB + (size_t)(row - 16384) * 2048) + col0; float s = 0.f;
; #pragma unroll
;                 for (int bj = 0; bj < 2; ++bj) { const f32x4 v0 = acc[ai][bj][m][0] * f + __builtin_nontemporal_load((const f32x4*)(src + bj * HALF)), v1 = acc[ai][bj][m][1] * f + __builtin_nontemporal_load((const f32x4*)(src + bj * HALF + 4));
;                     s += (v0[0] * v0[0] + v0[1] * v0[1]) + (v0[2] * v0[2] + v0[3] * v0[3]) + (v1[0] * v1[0] + v1[1] * v1[1]) + (v1[2] * v1[2] + v1[3] * v1[3]);
;                     u32x4 w; w.x = cvt_pk_bf16(v0[0], v0[1]); w.y = cvt_pk_bf16(v0[2], v0[3]); w.z = cvt_pk_bf16(v1[0], v1[1]); w.w = cvt_pk_bf16(v1[2], v1[3]);
;                     *(u32x4*)(xb + (size_t)row * 2048 + col0 + bj * HALF) = w; }
;                 s = sum_x32(sum_x16(s)); asm volatile("" : "+v"(s));
;                 if (fq == 0) atomicAdd(ss + row, s); }
	v_pk_fma_f32 v[44:45], v[44:45], v[56:57], v[48:49] op_sel_hi:[1,0,1]
	v_pk_fma_f32 v[42:43], v[42:43], v[56:57], v[46:47] op_sel_hi:[1,0,1]
	s_waitcnt vmcnt(0)
	v_pk_fma_f32 v[48:49], v[38:39], v[56:57], v[50:51] op_sel_hi:[1,0,1]
	v_mul_f32_e32 v50, v43, v43
	v_mul_f32_e32 v51, v45, v45
	v_pk_fma_f32 v[46:47], v[40:41], v[56:57], v[52:53] op_sel_hi:[1,0,1]
	v_mul_f32_e32 v52, v49, v49
	v_cvt_pk_bf16_f32 v38, v42, v43
	v_fmac_f32_e32 v50, v42, v42
	v_fmac_f32_e32 v51, v44, v44
	v_mul_f32_e32 v53, v47, v47
	v_cvt_pk_bf16_f32 v39, v44, v45
	v_cvt_pk_bf16_f32 v40, v48, v49
	v_cvt_pk_bf16_f32 v41, v46, v47
	v_fmac_f32_e32 v52, v48, v48
	global_store_dwordx4 v[68:69], v[38:41], off offset:256
	v_fmac_f32_e32 v53, v46, v46
	s_nop 0
	v_add_f32_e32 v38, v50, v51
	v_add_f32_e32 v38, v38, v52
	v_add_f32_e32 v38, v53, v38
	v_add_f32_e32 v3, v3, v38
	v_mov_b32_e32 v38, v3
	s_nop 1
	v_permlane16_swap_b32_e32 v3, v38
	v_add_f32_e32 v3, v3, v38
	v_mov_b32_e32 v38, v3
	s_nop 1
	v_permlane32_swap_b32_e32 v3, v38
	v_add_f32_e32 v3, v3, v38
	v_mov_b32_e32 v231, v3
	ds_read_b32 v40, v163 offset:2568
	v_add_u32_e32 v38, 0xa0, v150
	v_cmp_lt_i32_e32 vcc, s82, v150
	s_and_saveexec_b64 s[28:29], vcc
	s_xor_b64 s[28:29], exec, s[28:29]
	v_add_u32_e32 v42, 0xffffc0a0, v150
	v_mov_b32_e32 v43, v2
	v_lshlrev_b64 v[42:43], 13, v[42:43]
	v_lshl_add_u64 v[42:43], s[38:39], 0, v[42:43]
	v_mov_b32_e32 v39, v2
	s_andn2_saveexec_b64 s[28:29], s[28:29]
	v_ashrrev_i32_e32 v39, 31, v38
	v_lshlrev_b64 v[42:43], 13, v[38:39]
	v_lshl_add_u64 v[42:43], s[36:37], 0, v[42:43]
	s_or_b64 exec, exec, s[28:29]
	v_lshl_add_u64 v[50:51], v[4:5], 2, v[42:43]
	global_load_dwordx4 v[42:45], v[50:51], off nt
	global_load_dwordx4 v[46:49], v[50:51], off offset:16 nt
	v_lshlrev_b64 v[52:53], 12, v[38:39]
	v_lshl_add_u64 v[52:53], s[16:17], 0, v[52:53]
	v_lshl_add_u64 v[52:53], v[4:5], 1, v[52:53]
	s_waitcnt vmcnt(1) lgkmcnt(0)
	v_pk_fma_f32 v[44:45], v[36:37], v[40:41], v[44:45] op_sel_hi:[1,0,1]
	v_pk_fma_f32 v[42:43], v[34:35], v[40:41], v[42:43] op_sel_hi:[1,0,1]
	s_waitcnt vmcnt(0)
	v_pk_fma_f32 v[48:49], v[32:33], v[40:41], v[48:49] op_sel_hi:[1,0,1]
	v_pk_fma_f32 v[46:47], v[30:31], v[40:41], v[46:47] op_sel_hi:[1,0,1]
	v_cvt_pk_bf16_f32 v30, v42, v43
	v_cvt_pk_bf16_f32 v31, v44, v45
	v_mul_f32_e32 v41, v45, v45
	v_cvt_pk_bf16_f32 v32, v46, v47
	v_cvt_pk_bf16_f32 v33, v48, v49
	global_store_dwordx4 v[52:53], v[30:33], off
	global_load_dwordx4 v[30:33], v[50:51], off offset:512 nt
	s_nop 0
	global_load_dwordx4 v[34:37], v[50:51], off offset:528 nt
	v_fmac_f32_e32 v41, v44, v44
	v_mul_f32_e32 v3, v43, v43
	v_mul_f32_e32 v43, v47, v47
	v_fmac_f32_e32 v3, v42, v42
	v_mul_f32_e32 v45, v49, v49
	v_fmac_f32_e32 v43, v46, v46
	v_add_f32_e32 v3, v3, v41
	v_fmac_f32_e32 v45, v48, v48
	v_add_f32_e32 v3, v3, v43
	v_add_f32_e32 v3, v45, v3
	s_waitcnt vmcnt(1)
	v_pk_fma_f32 v[28:29], v[28:29], v[40:41], v[32:33] op_sel_hi:[1,0,1]
	v_pk_fma_f32 v[26:27], v[26:27], v[40:41], v[30:31] op_sel_hi:[1,0,1]
	s_waitcnt vmcnt(0)
; __device__ __forceinline__ unsigned cvt_pk_bf16(float lo, float hi) { unsigned r; asm volatile("v_cvt_pk_bf16_f32 %0, %1, %2" : "=v"(r) : "v"(lo), "v"(hi)); return r; }
;     __device__ __forceinline__ void final(const f32x4 (&acc)[2][2][4][2], const Unit& u, int ui, int wr, int wc, int fr, int fq) const {
;     ...
;             for (int m = 0; m < 4; ++m) { const int row = row0 + ai * HALF + m * 16; const float f = tab[(ui * 256 + ai * HALF + wr * 64 + m * 16 + fr) * 4 + 2];
;                 const float* src = (row < 16384 ? srcA + (size_t)row * 2048 : srcB + (size_t)(row - 16384) * 2048) + col0; float s = 0.f;
; #pragma unroll
;                 for (int bj = 0; bj < 2; ++bj) { const f32x4 v0 = acc[ai][bj][m][0] * f + __builtin_nontemporal_load((const f32x4*)(src + bj * HALF)), v1 = acc[ai][bj][m][1] * f + __builtin_nontemporal_load((const f32x4*)(src + bj * HALF + 4));
;                     s += (v0[0] * v0[0] + v0[1] * v0[1]) + (v0[2] * v0[2] + v0[3] * v0[3]) + (v1[0] * v1[0] + v1[1] * v1[1]) + (v1[2] * v1[2] + v1[3] * v1[3]);
;                     u32x4 w; w.x = cvt_pk_bf16(v0[0], v0[1]); w.y = cvt_pk_bf16(v0[2], v0[3]); w.z = cvt_pk_bf16(v1[0], v1[1]); w.w = cvt_pk_bf16(v1[2], v1[3]);
;                     *(u32x4*)(xb + (size_t)row * 2048 + col0 + bj * HALF) = w; }
;                 s = sum_x32(sum_x16(s)); asm volatile("" : "+v"(s));
;                 if (fq == 0) atomicAdd(ss + row, s); }
	v_pk_fma_f32 v[32:33], v[22:23], v[40:41], v[34:35] op_sel_hi:[1,0,1]
	v_mul_f32_e32 v34, v27, v27
	v_mul_f32_e32 v35, v29, v29
	v_pk_fma_f32 v[30:31], v[24:25], v[40:41], v[36:37] op_sel_hi:[1,0,1]
	v_mul_f32_e32 v36, v33, v33
	v_cvt_pk_bf16_f32 v22, v26, v27
	v_fmac_f32_e32 v34, v26, v26
	v_fmac_f32_e32 v35, v28, v28
	v_mul_f32_e32 v37, v31, v31
	v_cvt_pk_bf16_f32 v23, v28, v29
	v_cvt_pk_bf16_f32 v24, v32, v33
	v_cvt_pk_bf16_f32 v25, v30, v31
	v_fmac_f32_e32 v36, v32, v32
	global_store_dwordx4 v[52:53], v[22:25], off offset:256
	v_fmac_f32_e32 v37, v30, v30
	s_nop 0
	v_add_f32_e32 v22, v34, v35
	v_add_f32_e32 v22, v22, v36
	v_add_f32_e32 v22, v37, v22
	v_add_f32_e32 v3, v3, v22
	v_mov_b32_e32 v22, v3
	s_nop 1
	v_permlane16_swap_b32_e32 v3, v22
	v_add_f32_e32 v3, v3, v22
	v_mov_b32_e32 v22, v3
	s_nop 1
	v_permlane32_swap_b32_e32 v3, v22
	v_add_f32_e32 v3, v3, v22
	v_mov_b32_e32 v232, v3
	ds_read_b32 v24, v163 offset:2824
	v_add_u32_e32 v22, 0xb0, v150
	v_cmp_lt_i32_e32 vcc, s83, v150
	s_and_saveexec_b64 s[28:29], vcc
	s_xor_b64 s[28:29], exec, s[28:29]
	v_add_u32_e32 v26, 0xffffc0b0, v150
	v_mov_b32_e32 v27, v2
	v_lshlrev_b64 v[26:27], 13, v[26:27]
	v_lshl_add_u64 v[26:27], s[38:39], 0, v[26:27]
	v_mov_b32_e32 v23, v2
	s_andn2_saveexec_b64 s[28:29], s[28:29]
	v_ashrrev_i32_e32 v23, 31, v22
	v_lshlrev_b64 v[26:27], 13, v[22:23]
	v_lshl_add_u64 v[26:27], s[36:37], 0, v[26:27]
	s_or_b64 exec, exec, s[28:29]
	v_lshl_add_u64 v[34:35], v[4:5], 2, v[26:27]
	global_load_dwordx4 v[26:29], v[34:35], off nt
	global_load_dwordx4 v[30:33], v[34:35], off offset:16 nt
	v_lshlrev_b64 v[36:37], 12, v[22:23]
	v_lshl_add_u64 v[36:37], s[16:17], 0, v[36:37]
	v_lshl_add_u64 v[36:37], v[4:5], 1, v[36:37]
	s_waitcnt vmcnt(1) lgkmcnt(0)
	v_pk_fma_f32 v[4:5], v[20:21], v[24:25], v[28:29] op_sel_hi:[1,0,1]
	v_pk_fma_f32 v[26:27], v[18:19], v[24:25], v[26:27] op_sel_hi:[1,0,1]
	s_waitcnt vmcnt(0)
	v_pk_fma_f32 v[28:29], v[16:17], v[24:25], v[32:33] op_sel_hi:[1,0,1]
	v_pk_fma_f32 v[30:31], v[14:15], v[24:25], v[30:31] op_sel_hi:[1,0,1]
	v_cvt_pk_bf16_f32 v14, v26, v27
	v_cvt_pk_bf16_f32 v15, v4, v5
	v_mul_f32_e32 v3, v27, v27
	v_cvt_pk_bf16_f32 v16, v30, v31
	v_cvt_pk_bf16_f32 v17, v28, v29
	global_store_dwordx4 v[36:37], v[14:17], off
	global_load_dwordx4 v[14:17], v[34:35], off offset:512 nt
	s_nop 0
	global_load_dwordx4 v[18:21], v[34:35], off offset:528 nt
	v_mul_f32_e32 v25, v31, v31
	v_fmac_f32_e32 v25, v30, v30
	v_mul_f32_e32 v5, v5, v5
	v_fmac_f32_e32 v3, v26, v26
	v_fmac_f32_e32 v5, v4, v4
	v_mul_f32_e32 v27, v29, v29
	v_add_f32_e32 v3, v3, v5
	v_fmac_f32_e32 v27, v28, v28
	v_add_f32_e32 v3, v3, v25
	v_add_f32_e32 v3, v27, v3
	s_waitcnt vmcnt(1)
	v_pk_fma_f32 v[12:13], v[12:13], v[24:25], v[16:17] op_sel_hi:[1,0,1]
	v_pk_fma_f32 v[10:11], v[10:11], v[24:25], v[14:15] op_sel_hi:[1,0,1]
	s_waitcnt vmcnt(0)
	v_pk_fma_f32 v[14:15], v[6:7], v[24:25], v[18:19] op_sel_hi:[1,0,1]
	v_mul_f32_e32 v16, v11, v11
	v_mul_f32_e32 v17, v13, v13
	v_pk_fma_f32 v[8:9], v[8:9], v[24:25], v[20:21] op_sel_hi:[1,0,1]
	v_mul_f32_e32 v18, v15, v15
	v_cvt_pk_bf16_f32 v4, v10, v11
	v_fmac_f32_e32 v16, v10, v10
	v_fmac_f32_e32 v17, v12, v12
	v_mul_f32_e32 v19, v9, v9
	v_cvt_pk_bf16_f32 v5, v12, v13
	v_cvt_pk_bf16_f32 v6, v14, v15
	v_cvt_pk_bf16_f32 v7, v8, v9
	v_fmac_f32_e32 v18, v14, v14
	global_store_dwordx4 v[36:37], v[4:7], off offset:256
	v_fmac_f32_e32 v19, v8, v8
	s_nop 0
	v_add_f32_e32 v4, v16, v17
	v_add_f32_e32 v4, v4, v18
	v_add_f32_e32 v4, v19, v4
	v_add_f32_e32 v3, v3, v4
	v_mov_b32_e32 v4, v3
	s_nop 1
	v_permlane16_swap_b32_e32 v3, v4
	v_add_f32_e32 v3, v3, v4
	v_mov_b32_e32 v4, v3
	s_nop 1
	v_permlane32_swap_b32_e32 v3, v4
	v_add_f32_e32 v3, v3, v4
	v_mov_b32_e32 v233, v3
	s_and_saveexec_b64 s[28:29], s[2:3]
	global_atomic_add_f32 v[250:251], v226, off
	global_atomic_add_f32 v[250:251], v227, off offset:64
	global_atomic_add_f32 v[250:251], v228, off offset:128
	global_atomic_add_f32 v[250:251], v229, off offset:192
	global_atomic_add_f32 v[250:251], v230, off offset:512
	global_atomic_add_f32 v[250:251], v231, off offset:576
	global_atomic_add_f32 v[250:251], v232, off offset:640
	global_atomic_add_f32 v[250:251], v233, off offset:704
	s_or_b64 exec, exec, s[28:29]
	s_andn2_b64 vcc, exec, s[4:5]
	s_mov_b64 s[4:5], -1
	s_cbranch_vccnz .LBB0_405
	s_andn2_b64 vcc, exec, s[6:7]
	s_cbranch_vccnz .LBB0_404
	s_barrier
	s_branch .LBB0_404
